# scan does not fetch the 32-token groups of the intra-chunk score tile that are zero by the causal / anti-causal mask for a wave's rows (their MFMA operand registers stay zero)
# speedup vs baseline: 1.0050x; 1.0050x over previous
.LBB0_1220:
	s_or_b64 exec, exec, s[12:13]
	s_waitcnt vmcnt(8)
	v_mul_f32_e32 v40, 0x3fb8aa3b, v40
	v_exp_f32_e32 v46, v40
	s_lshl_b64 s[10:11], s[10:11], 13
	v_lshl_add_u64 v[40:41], s[10:11], 0, v[120:121]
	v_or_b32_e32 v42, v40, v124
	v_mul_f32_e32 v43, 0xc3000000, v46
	v_mul_f32_e32 v47, 0x3fb8aa3b, v43
	v_mov_b32_e32 v43, v41
	v_readlane_b32 s10, v251, 38
	v_lshlrev_b64 v[42:43], 11, v[42:43]
	v_readlane_b32 s11, v251, 39
	s_lshl_b32 s82, s19, 1
	s_lshl_b64 s[8:9], s[8:9], 21
	v_lshl_add_u64 v[42:43], s[10:11], 0, v[42:43]
	v_lshl_add_u64 v[42:43], v[42:43], 0, s[82:83]
	s_lshl_b32 s82, s17, 1
	s_cmpk_lt_u32 s16, 0x80
	s_cselect_b64 vcc, -1, 0
	v_cndmask_b32_e32 v48, v186, v187, vcc
	v_cvt_f32_i32_e32 v48, v48
	v_cndmask_b32_e32 v49, v188, v189, vcc
	v_cvt_f32_i32_e32 v49, v49
	v_or_b32_e32 v44, v40, v134
	v_mul_f32_e64 v48, -v46, v48
	v_mul_f32_e32 v48, 0x3fb8aa3b, v48
	v_exp_f32_e32 v226, v48
	v_mul_f32_e64 v48, -v46, v49
	v_mul_f32_e32 v48, 0x3fb8aa3b, v48
	v_cndmask_b32_e32 v49, v190, v191, vcc
	v_exp_f32_e32 v227, v48
	v_cndmask_b32_e32 v48, v192, v193, vcc
	v_cvt_f32_i32_e32 v49, v49
	v_cvt_f32_i32_e32 v48, v48
	v_mov_b32_e32 v45, v41
	v_readlane_b32 s10, v251, 2
	v_lshlrev_b64 v[44:45], 12, v[44:45]
	v_readlane_b32 s11, v251, 3
	v_or_b32_e32 v40, v40, v136
	v_lshlrev_b64 v[40:41], 9, v[40:41]
	v_lshl_add_u64 v[44:45], s[10:11], 0, v[44:45]
	v_readlane_b32 s10, v252, 24
	v_readlane_b32 s11, v252, 25
	v_mul_f32_e64 v49, -v46, v49
	v_mul_f32_e64 v46, -v46, v48
	v_lshl_add_u64 v[44:45], v[44:45], 0, s[82:83]
	v_lshl_add_u64 v[40:41], s[10:11], 0, v[40:41]
	v_mul_f32_e32 v49, 0x3fb8aa3b, v49
	v_mul_f32_e32 v46, 0x3fb8aa3b, v46
	v_exp_f32_e32 v146, v47
	s_lshl_b32 s82, s15, 7
	v_exp_f32_e32 v228, v49
	v_exp_f32_e32 v229, v46
	v_lshl_add_u64 v[40:41], v[40:41], 0, s[82:83]
	s_lshl_b32 s82, s14, 2
	v_mov_b32_e32 v139, v1
	v_lshl_add_u64 v[150:151], v[130:131], 0, s[8:9]
	v_mov_b32_e32 v141, v1
	s_and_b64 s[8:9], s[6:7], exec
	v_lshl_add_u64 v[148:149], v[42:43], 0, v[138:139]
	v_lshl_add_u64 v[152:153], v[44:45], 0, v[140:141]
	v_lshl_add_u64 v[154:155], v[40:41], 0, s[82:83]
	s_movk_i32 s8, 0x2080
	v_mov_b32_e32 v48, v1
	v_mov_b32_e32 v49, v1
	v_mov_b32_e32 v92, 0
	v_mov_b64_e32 v[46:47], v[2:3]
	v_mov_b64_e32 v[42:43], v[2:3]
	v_mov_b64_e32 v[70:71], v[2:3]
	v_mov_b64_e32 v[74:75], v[2:3]
	v_mov_b64_e32 v[78:79], v[2:3]
	v_mov_b64_e32 v[82:83], v[2:3]
	v_mov_b32_e32 v156, v146
	v_mov_b32_e32 v157, v146
	s_cselect_b32 s19, 0x2000, s8
	s_mov_b32 s9, -2
	s_mov_b32 s20, 64
	v_mov_b64_e32 v[44:45], v[0:1]
	v_mov_b64_e32 v[40:41], v[0:1]
	v_mov_b64_e32 v[68:69], v[0:1]
	v_mov_b64_e32 v[72:73], v[0:1]
	v_mov_b64_e32 v[76:77], v[0:1]
	v_mov_b64_e32 v[80:81], v[0:1]
	v_mov_b64_e32 v[66:67], v[48:49]
	v_mov_b64_e32 v[64:65], v[48:49]
	v_mov_b64_e32 v[86:87], v[48:49]
	v_mov_b64_e32 v[84:85], v[48:49]
	v_mov_b64_e32 v[90:91], v[48:49]
	v_mov_b64_e32 v[88:89], v[48:49]
	v_mov_b64_e32 v[50:51], v[48:49]
	v_mov_b64_e32 v[60:61], v[48:49]
	v_mov_b64_e32 v[62:63], v[48:49]
	v_mov_b64_e32 v[56:57], v[48:49]
	v_mov_b64_e32 v[58:59], v[48:49]
	v_mov_b64_e32 v[52:53], v[48:49]
	v_mov_b64_e32 v[54:55], v[48:49]
	v_mov_b32_e32 v93, v92
	v_mov_b32_e32 v94, v92
	v_mov_b32_e32 v95, v92
	v_mov_b32_e32 v96, v92
	v_mov_b32_e32 v97, v92
	v_mov_b32_e32 v98, v92
	v_mov_b32_e32 v99, v92
	v_lshrrev_b32_e32 v100, 7, v200
	s_nop 0
	v_readfirstlane_b32 s101, v100
	s_lshl_b32 s98, 2, s101
	s_add_i32 s98, s98, -1
	s_lshl_b32 s99, 15, s101
	s_and_b32 s99, s99, 15
	s_cmpk_gt_u32 s16, 0x7f
	s_cselect_b32 s101, s99, s98
	s_branch .LBB0_1222

.LBB0_1226:
	s_cmp_gt_u32 s13, 1
	s_cselect_b64 s[14:15], -1, 0
	s_and_b32 s12, s13, 1
	s_cmp_lt_u32 s13, 2
	s_mul_i32 s22, s12, 0x2100
	s_cbranch_scc1 .Lscan_nl
	s_waitcnt vmcnt(14)
	ds_write_b128 v194, v[44:47]
	ds_write_b128 v195, v[52:55]
	ds_write_b128 v196, v[56:59]
	ds_write_b128 v197, v[60:63]
	ds_write_b128 v198, v[48:51]
	ds_write_b128 v199, v[64:67]
	ds_write_b128 v201, v[84:87]
	ds_write_b128 v220, v[88:91]
	s_and_saveexec_b64 s[10:11], s[2:3]
	ds_write_b128 v137, v[40:43]
	s_or_b64 exec, exec, s[10:11]
	v_and_b32_sdwa v3, v92, v204 dst_sel:DWORD dst_unused:UNUSED_PAD src0_sel:WORD_1 src1_sel:DWORD
	v_add3_u32 v100, v92, v3, s33
	v_and_b32_sdwa v3, v95, v204 dst_sel:DWORD dst_unused:UNUSED_PAD src0_sel:WORD_1 src1_sel:DWORD
	v_and_b32_sdwa v101, v93, v204 dst_sel:DWORD dst_unused:UNUSED_PAD src0_sel:WORD_1 src1_sel:DWORD
	v_and_b32_sdwa v2, v94, v204 dst_sel:DWORD dst_unused:UNUSED_PAD src0_sel:WORD_1 src1_sel:DWORD
	v_add3_u32 v3, v95, v3, s33
	v_add3_u32 v101, v93, v101, s33
	v_add3_u32 v2, v94, v2, s33
	v_and_b32_e32 v3, 0xffff0000, v3
	v_and_b32_e32 v101, 0xffff0000, v101
	v_or_b32_sdwa v3, v3, v2 dst_sel:DWORD dst_unused:UNUSED_PAD src0_sel:DWORD src1_sel:WORD_1
	v_or_b32_sdwa v2, v101, v100 dst_sel:DWORD dst_unused:UNUSED_PAD src0_sel:DWORD src1_sel:WORD_1
	v_and_b32_sdwa v101, v96, v204 dst_sel:DWORD dst_unused:UNUSED_PAD src0_sel:WORD_1 src1_sel:DWORD
	v_add3_u32 v102, v96, v101, s33
	v_and_b32_sdwa v101, v99, v204 dst_sel:DWORD dst_unused:UNUSED_PAD src0_sel:WORD_1 src1_sel:DWORD
	v_and_b32_sdwa v103, v97, v204 dst_sel:DWORD dst_unused:UNUSED_PAD src0_sel:WORD_1 src1_sel:DWORD
	v_and_b32_sdwa v100, v98, v204 dst_sel:DWORD dst_unused:UNUSED_PAD src0_sel:WORD_1 src1_sel:DWORD
	v_add3_u32 v101, v99, v101, s33
	v_add3_u32 v103, v97, v103, s33
	v_add3_u32 v100, v98, v100, s33
	v_and_b32_e32 v101, 0xffff0000, v101
	v_and_b32_e32 v103, 0xffff0000, v103
	v_add_u32_e32 v0, s22, v179
	v_or_b32_sdwa v101, v101, v100 dst_sel:DWORD dst_unused:UNUSED_PAD src0_sel:DWORD src1_sel:WORD_1
	v_or_b32_sdwa v100, v103, v102 dst_sel:DWORD dst_unused:UNUSED_PAD src0_sel:DWORD src1_sel:WORD_1
	ds_write2_b64 v0, v[2:3], v[100:101] offset1:4

.LBB0_1242:
	s_or_b64 exec, exec, s[16:17]
	v_lshl_add_u32 v0, s23, 1, v158
	v_lshl_add_u32 v2, v159, 1, v0
	s_waitcnt lgkmcnt(0)
	s_barrier
	v_lshl_add_u32 v3, v160, 1, v0
	ds_read_b128 v[112:115], v2
	ds_read_b128 v[108:111], v3
	v_lshl_add_u32 v2, v161, 1, v0
	v_lshl_add_u32 v0, v162, 1, v0
	ds_read_b128 v[104:107], v2
	ds_read_b128 v[100:103], v0
	s_andn2_b64 vcc, exec, s[14:15]
	s_cbranch_vccnz .LBB0_1248
	s_setprio 1
	v_add_u32_e32 v0, s22, v181
	v_add_u32_e32 v2, v180, v163
	v_add_u32_e32 v3, v180, v165
	ds_read_b128 v[238:241], v2
	ds_read_b128 v[242:245], v0
	ds_read_b128 v[246:249], v3
	ds_read_b128 v[116:119], v0 offset:64
	v_add_u32_e32 v2, v180, v169
	v_add_u32_e32 v3, v180, v173
	s_waitcnt lgkmcnt(2)
	v_mfma_f32_16x16x32_bf16 v[234:237], v[238:241], v[242:245], 0
	ds_read_b128 v[238:241], v2
	ds_read_b128 v[242:245], v0 offset:128
	s_waitcnt lgkmcnt(2)
	v_mfma_f32_16x16x32_bf16 v[230:233], v[246:249], v[116:119], 0
	ds_read_b128 v[246:249], v3
	ds_read_b128 v[116:119], v0 offset:192
	s_waitcnt lgkmcnt(2)
	v_mfma_f32_16x16x32_bf16 v[234:237], v[238:241], v[242:245], v[234:237]
	ds_read_b128 v[238:241], v221
	ds_read_b128 v[242:245], v0 offset:256
	s_waitcnt lgkmcnt(2)
	v_mfma_f32_16x16x32_bf16 v[230:233], v[246:249], v[116:119], v[230:233]
	ds_read_b128 v[246:249], v222
	ds_read_b128 v[116:119], v0 offset:320
	s_waitcnt lgkmcnt(2)
	v_mfma_f32_16x16x32_bf16 v[234:237], v[238:241], v[242:245], v[234:237]
	ds_read_b128 v[238:241], v223
	ds_read_b128 v[242:245], v0 offset:384
	s_waitcnt lgkmcnt(2)
	v_mfma_f32_16x16x32_bf16 v[230:233], v[246:249], v[116:119], v[230:233]
	ds_read_b128 v[246:249], v224
	ds_read_b128 v[116:119], v0 offset:448
	s_waitcnt lgkmcnt(2)
	v_mfma_f32_16x16x32_bf16 v[234:237], v[238:241], v[242:245], v[234:237]
	s_waitcnt lgkmcnt(0)
	v_mfma_f32_16x16x32_bf16 v[230:233], v[246:249], v[116:119], v[230:233]
	s_waitcnt vmcnt(22)
	v_mfma_f32_16x16x32_bf16 v[116:119], v[80:83], v[112:115], 0
	v_mfma_f32_16x16x32_bf16 v[116:119], v[76:79], v[108:111], v[116:119]
	v_mfma_f32_16x16x32_bf16 v[116:119], v[72:75], v[104:107], v[116:119]
	v_mfma_f32_16x16x32_bf16 v[116:119], v[68:71], v[100:103], v[116:119]
	s_setprio 0
	s_cmp_eq_u32 s100, 0
	s_cbranch_scc1 .Lscan_ldq_donea
	s_mov_b32 s16, s99
	s_mov_b32 s17, 0
	v_lshl_add_u64 v[2:3], v[150:151], 0, s[16:17]
	s_bitcmp0_b32 s101, 0
	s_cbranch_scc1 .Lscan_tria0
	global_load_dwordx4 v[80:83], v[2:3], off
.Lscan_tria0:
	s_bitcmp0_b32 s101, 1
	s_cbranch_scc1 .Lscan_tria1
	global_load_dwordx4 v[76:79], v[2:3], off offset:1024
.Lscan_tria1:
	s_bitcmp0_b32 s101, 2
	s_cbranch_scc1 .Lscan_tria2
	global_load_dwordx4 v[72:75], v[2:3], off offset:2048
.Lscan_tria2:
	s_bitcmp0_b32 s101, 3
	s_cbranch_scc1 .Lscan_tria3
	global_load_dwordx4 v[68:71], v[2:3], off offset:3072
.Lscan_tria3:
.Lscan_ldq_donea:
	v_add_f32_e32 v0, v234, v230
	s_nop 5
	v_fma_f32 v3, v226, v0, v116
	v_add_f32_e32 v0, v235, v231
	v_fma_f32 v2, v227, v0, v117
	v_add_f32_e32 v0, v236, v232
	v_add_f32_e32 v116, v237, v233
	v_fma_f32 v0, v228, v0, v118
	v_fmac_f32_e32 v119, v229, v116
	v_mul_f32_e32 v116, v3, v3
	v_mul_f32_e32 v118, v2, v2
	v_mul_f32_e32 v141, v0, v0
	v_mul_f32_e32 v230, v119, v119
	v_mov_b32_dpp v116, v116 quad_perm:[1,0,3,2] row_mask:0xf bank_mask:0xf bound_ctrl:1
	v_mov_b32_dpp v118, v118 quad_perm:[1,0,3,2] row_mask:0xf bank_mask:0xf bound_ctrl:1
	v_mov_b32_dpp v141, v141 quad_perm:[1,0,3,2] row_mask:0xf bank_mask:0xf bound_ctrl:1
	v_mov_b32_dpp v230, v230 quad_perm:[1,0,3,2] row_mask:0xf bank_mask:0xf bound_ctrl:1
	v_fmac_f32_e32 v116, v3, v3
	v_fmac_f32_e32 v118, v2, v2
	v_fmac_f32_e32 v141, v0, v0
	v_fmac_f32_e32 v230, v119, v119
	v_add_f32_dpp v116, v116, v116 quad_perm:[2,3,0,1] row_mask:0xf bank_mask:0xf bound_ctrl:1
	v_add_f32_dpp v118, v118, v118 quad_perm:[2,3,0,1] row_mask:0xf bank_mask:0xf bound_ctrl:1
	v_add_f32_dpp v141, v141, v141 quad_perm:[2,3,0,1] row_mask:0xf bank_mask:0xf bound_ctrl:1
	v_add_f32_dpp v230, v230, v230 quad_perm:[2,3,0,1] row_mask:0xf bank_mask:0xf bound_ctrl:1
	v_add_f32_dpp v116, v116, v116 row_half_mirror row_mask:0xf bank_mask:0xf bound_ctrl:1
	v_add_f32_dpp v118, v118, v118 row_half_mirror row_mask:0xf bank_mask:0xf bound_ctrl:1
	v_add_f32_dpp v141, v141, v141 row_half_mirror row_mask:0xf bank_mask:0xf bound_ctrl:1
	v_add_f32_dpp v230, v230, v230 row_half_mirror row_mask:0xf bank_mask:0xf bound_ctrl:1
	v_mov_b32_dpp v117, v116 row_mirror row_mask:0xf bank_mask:0xf bound_ctrl:1
	v_mov_b32_dpp v139, v118 row_mirror row_mask:0xf bank_mask:0xf bound_ctrl:1
	v_mov_b32_dpp v147, v141 row_mirror row_mask:0xf bank_mask:0xf bound_ctrl:1
	v_mov_b32_dpp v231, v230 row_mirror row_mask:0xf bank_mask:0xf bound_ctrl:1
	s_and_saveexec_b64 s[14:15], s[4:5]
	s_cbranch_execz .LBB0_1245
	s_ashr_i32 s9, s8, 31
	s_lshl_b64 s[16:17], s[8:9], 9
	v_lshl_add_u64 v[232:233], v[154:155], 0, s[16:17]
	v_add_f32_e32 v116, v116, v117
	v_add_f32_e32 v230, v230, v231
	v_add_f32_e32 v141, v141, v147
	v_add_f32_e32 v118, v118, v139
	global_store_dword v[232:233], v116, off
	global_store_dword v[232:233], v118, off offset:512
	global_store_dword v[232:233], v141, off offset:1024
	global_store_dword v[232:233], v230, off offset:1536

.LBB0_1247:
	s_or_b64 exec, exec, s[14:15]
	s_andn2_b64 vcc, exec, s[12:13]
	s_cbranch_vccnz .Lscan_w0
	s_waitcnt vmcnt(15)
	s_branch .Lscan_kw
.LBB0_1248:
	s_cmp_eq_u32 s100, 0
	s_cbranch_scc1 .Lscan_ldq_doneb
	s_mov_b32 s16, s99
	s_mov_b32 s17, 0
	v_lshl_add_u64 v[2:3], v[150:151], 0, s[16:17]
	s_bitcmp0_b32 s101, 0
	s_cbranch_scc1 .Lscan_trib0
	global_load_dwordx4 v[80:83], v[2:3], off

.Lscan_trib3:
.Lscan_ldq_doneb:
	s_andn2_b64 vcc, exec, s[12:13]
